# GEMM: dedicated straight-line epilogue for the E_ST16 (FFN up-projection) tiles instead of the per-block mode switch
# speedup vs baseline: 1.0639x; 1.0036x over previous
; __device__ __forceinline__ u32x4 pack8(f32x4 a, f32x4 b) { u32x4 w; w.x = pk2(a[0], a[1]); w.y = pk2(a[2], a[3]); w.z = pk2(b[0], b[1]); w.w = pk2(b[2], b[3]); return w; }
;     __device__ __forceinline__ void operator()(const f32x4 (&acc)[2][2][4][2], const Unit& u, int wr, int wc, int fr, int fq) const {
;     ...
; #pragma unroll
;         for (int ai = 0; ai < 2; ++ai)
; #pragma unroll
;             for (int m = 0; m < 4; ++m) {
;                 const int rowl = rowl0 + ai * HALF + m * 16;
;                 const int rowg = rowl + pm0 * BM;
; #pragma unroll
;                 for (int bj = 0; bj < 2; ++bj) {
;                     const int col = colt + bj * HALF;
;                     f32x4 v0 = acc[ai][bj][m][0], v1 = acc[ai][bj][m][1];
;     ...
;                     } else if (mode == E_ST16) {
;                         *(u32x4*)((h16*)(ws + F_U16) + (size_t)rowl * 5632 + col) = pack8(v0, v1);
.Lst16_fast:
	v_readlane_b32 s0, v251, 1
	v_readlane_b32 s1, v251, 2
	s_movk_i32 s33, 0x2c00
	v_mad_i64_i32 v[128:129], s[38:39], v240, s33, 0
	v_ashrrev_i32_e32 v217, 31, v216
	v_lshl_add_u64 v[128:129], s[0:1], 0, v[128:129]
	v_lshl_add_u64 v[128:129], v[216:217], 1, v[128:129]
	s_mov_b32 s34, 0x2c000
	s_mov_b32 s35, 0
	s_mov_b32 s36, 0xdc000
	s_mov_b32 s37, 0
	v_cvt_pk_f16_f32 v132, v124, v125
	v_cvt_pk_f16_f32 v133, v126, v127
	v_cvt_pk_f16_f32 v134, v120, v121
	v_cvt_pk_f16_f32 v135, v122, v123
	v_lshl_add_u64 v[130:131], v[128:129], 0, s[34:35]
	global_store_dwordx4 v[128:129], v[132:135], off
	v_cvt_pk_f16_f32 v136, v116, v117
	v_cvt_pk_f16_f32 v137, v118, v119
	v_cvt_pk_f16_f32 v138, v112, v113
	v_cvt_pk_f16_f32 v139, v114, v115
	global_store_dwordx4 v[128:129], v[136:139], off offset:256
	v_cvt_pk_f16_f32 v132, v108, v109
	v_cvt_pk_f16_f32 v133, v110, v111
	v_cvt_pk_f16_f32 v134, v104, v105
	v_cvt_pk_f16_f32 v135, v106, v107
	v_lshl_add_u64 v[128:129], v[130:131], 0, s[34:35]
	global_store_dwordx4 v[130:131], v[132:135], off
	v_cvt_pk_f16_f32 v136, v100, v101
	v_cvt_pk_f16_f32 v137, v102, v103
	v_cvt_pk_f16_f32 v138, v96, v97
	v_cvt_pk_f16_f32 v139, v98, v99
	global_store_dwordx4 v[130:131], v[136:139], off offset:256
	v_cvt_pk_f16_f32 v132, v92, v93
	v_cvt_pk_f16_f32 v133, v94, v95
	v_cvt_pk_f16_f32 v134, v88, v89
	v_cvt_pk_f16_f32 v135, v90, v91
	v_lshl_add_u64 v[130:131], v[128:129], 0, s[34:35]
	global_store_dwordx4 v[128:129], v[132:135], off
	v_cvt_pk_f16_f32 v136, v84, v85
	v_cvt_pk_f16_f32 v137, v86, v87
	v_cvt_pk_f16_f32 v138, v80, v81
	v_cvt_pk_f16_f32 v139, v82, v83
	global_store_dwordx4 v[128:129], v[136:139], off offset:256
	v_cvt_pk_f16_f32 v132, v76, v77
	v_cvt_pk_f16_f32 v133, v78, v79
	v_cvt_pk_f16_f32 v134, v72, v73
	v_cvt_pk_f16_f32 v135, v74, v75
	v_lshl_add_u64 v[128:129], v[130:131], 0, s[36:37]
	global_store_dwordx4 v[130:131], v[132:135], off
	v_cvt_pk_f16_f32 v136, v68, v69
	v_cvt_pk_f16_f32 v137, v70, v71
	v_cvt_pk_f16_f32 v138, v64, v65
	v_cvt_pk_f16_f32 v139, v66, v67
	global_store_dwordx4 v[130:131], v[136:139], off offset:256
	v_cvt_pk_f16_f32 v132, v60, v61
	v_cvt_pk_f16_f32 v133, v62, v63
	v_cvt_pk_f16_f32 v134, v56, v57
	v_cvt_pk_f16_f32 v135, v58, v59
	v_lshl_add_u64 v[130:131], v[128:129], 0, s[34:35]
	global_store_dwordx4 v[128:129], v[132:135], off
	v_cvt_pk_f16_f32 v136, v52, v53
	v_cvt_pk_f16_f32 v137, v54, v55
	v_cvt_pk_f16_f32 v138, v48, v49
	v_cvt_pk_f16_f32 v139, v50, v51
	global_store_dwordx4 v[128:129], v[136:139], off offset:256
	v_cvt_pk_f16_f32 v132, v44, v45
	v_cvt_pk_f16_f32 v133, v46, v47
	v_cvt_pk_f16_f32 v134, v40, v41
	v_cvt_pk_f16_f32 v135, v42, v43
	v_lshl_add_u64 v[128:129], v[130:131], 0, s[34:35]
	global_store_dwordx4 v[130:131], v[132:135], off
	v_cvt_pk_f16_f32 v136, v36, v37
	v_cvt_pk_f16_f32 v137, v38, v39
	v_cvt_pk_f16_f32 v138, v32, v33
	v_cvt_pk_f16_f32 v139, v34, v35
	global_store_dwordx4 v[130:131], v[136:139], off offset:256
	v_cvt_pk_f16_f32 v132, v28, v29
	v_cvt_pk_f16_f32 v133, v30, v31
	v_cvt_pk_f16_f32 v134, v24, v25
	v_cvt_pk_f16_f32 v135, v26, v27
	v_lshl_add_u64 v[130:131], v[128:129], 0, s[34:35]
	global_store_dwordx4 v[128:129], v[132:135], off
	v_cvt_pk_f16_f32 v136, v20, v21
	v_cvt_pk_f16_f32 v137, v22, v23
	v_cvt_pk_f16_f32 v138, v16, v17
	v_cvt_pk_f16_f32 v139, v18, v19
	global_store_dwordx4 v[128:129], v[136:139], off offset:256
	v_cvt_pk_f16_f32 v132, v12, v13
	v_cvt_pk_f16_f32 v133, v14, v15
	v_cvt_pk_f16_f32 v134, v8, v9
	v_cvt_pk_f16_f32 v135, v10, v11
	global_store_dwordx4 v[130:131], v[132:135], off
	v_cvt_pk_f16_f32 v136, v4, v5
	v_cvt_pk_f16_f32 v137, v6, v7
	v_cvt_pk_f16_f32 v138, v0, v1
	v_cvt_pk_f16_f32 v139, v2, v3
	global_store_dwordx4 v[130:131], v[136:139], off offset:256

; #define PG8_STAGE(bufoff, gbase, voff) do { _Pragma("unroll") for (int _i = 0; _i < 2; ++_i) \
;         __builtin_amdgcn_global_load_lds((const unsigned*)((const char*)(gbase) + (voff)[_i]), (LAS unsigned*)(lds + (bufoff) + ldsw + _i * 8192), 16, 0, 0); } while (0)
; #define PG8_LDA(dst, b, h) do { _Pragma("unroll") for (int m = 0; m < 4; ++m) _Pragma("unroll") for (int k = 0; k < 2; ++k) dst[m][k] = *(const LAS h16x8*)(lds + PG8_SA(b, h) + aoff + m * 2048 + k * 1024); } while (0)
; #define PG8_LDB(dst, b, h) do { _Pragma("unroll") for (int n = 0; n < 2; ++n) _Pragma("unroll") for (int k = 0; k < 2; ++k) dst[n][k] = *(const LAS h16x8*)(lds + PG8_SB(b, h) + boff + n * 2048 + k * 1024); } while (0)
; #define PG8_MMA(ai, bj, At, Bt) do { __builtin_amdgcn_s_setprio(1); _Pragma("unroll") for (int m = 0; m < 4; ++m) _Pragma("unroll") for (int n = 0; n < 2; ++n) _Pragma("unroll") for (int k = 0; k < 2; ++k) \
;         acc[ai][bj][m][n] = __builtin_amdgcn_mfma_f32_16x16x32_f16(Bt[n][k], At[m][k], acc[ai][bj][m][n], 0, 0, 0); __builtin_amdgcn_s_setprio(0); } while (0)
; #define PG8_WAIT_L(n) asm volatile("s_waitcnt lgkmcnt(" #n ")" ::: "memory")
; #define PG8_BAR __builtin_amdgcn_s_barrier()
; #define PG8_SCHED __builtin_amdgcn_sched_barrier(0)
; __device__ __forceinline__ void gemm_phase(LAS unsigned char* lds, const Gemm g, const StaticOrder& S, const Epi& E) {
;     ...
;         for (int t = 0; t < nt; t += 2) {
;             const bool last = (t == nt - 2);
;             const char* a1 = cA + PG8_KOFF(t + 1);
;             const char* a2 = last ? nA : cA + PG8_KOFF(t + 2); const char* b2 = last ? nB : cB + (size_t)(t + 2) * kstep;
;             const char* a3 = a2 + kstep; const char* b3 = b2 + kstep;
;             PG8_LDB(B0, 0, 0); PG8_SCHED; PG8_LDA(At, 0, 0); PG8_STAGE(PG8_SA(1, 1), a1 + hstepA, voffA);
;             PG8_WAIT_L(8); PG8_BAR; PG8_WAIT_L(0); PG8_MMA(0, 0, At, B0); PG8_BAR; PG8_SCHED;
;             PG8_LDB(B1, 0, 1); PG8_STAGE(PG8_SB(0, 0), b2, voffB);
;             PG8_BAR; PG8_WAIT_L(0); PG8_MMA(0, 1, At, B1); PG8_BAR;
;             PG8_LDA(At, 0, 1); PG8_STAGE(PG8_SA(0, 0), a2, voffA);
;             PG8_BAR; PG8_WAIT_L(0); PG8_MMA(1, 0, At, B0); PG8_BAR; PG8_SCHED;
.LBB0_762:
	s_cmp_gt_u32 s34, 15
	s_cselect_b64 s[36:37], -1, 0
	s_and_b64 s[36:37], s[6:7], s[36:37]
	s_and_b64 s[36:37], s[36:37], exec
	s_cselect_b32 s42, 0xfffff000, 0
	s_cselect_b32 s43, -1, 0
	s_add_i32 s38, s34, 2
	s_cmp_gt_u32 s34, 13
	s_cselect_b64 s[36:37], -1, 0
	s_and_b64 s[36:37], s[6:7], s[36:37]
	s_and_b64 s[36:37], s[36:37], exec
	s_cselect_b32 s36, 0xfffff000, 0
	s_cselect_b32 s35, -1, 0
	s_add_u32 s36, s0, s36
	s_addc_u32 s35, s1, s35
	s_add_u32 s36, s36, 0x80
	s_addc_u32 s35, s35, 0
	s_add_i32 s39, 0, 0x10000
	v_add_u32_e32 v140, s39, v238
	ds_read_b128 v[128:131], v140
	ds_read_b128 v[132:135], v140 offset:1024
	ds_read_b128 v[136:139], v140 offset:2048
	ds_read_b128 v[140:143], v140 offset:3072
	s_cmp_eq_u32 s66, s34
	s_cselect_b32 s34, s4, s36
	s_cselect_b32 s35, s5, s35
	s_cselect_b32 s37, s29, s33
	s_cselect_b32 s36, s28, s27
	v_lshl_add_u64 v[176:177], s[0:1], 0, v[212:213]
	v_lshl_add_u64 v[176:177], v[176:177], 0, s[42:43]
	s_add_i32 m0, s58, 0xc000
	ds_read_b128 v[144:147], v239
	ds_read_b128 v[148:151], v239 offset:1024
	ds_read_b128 v[152:155], v239 offset:2048
	ds_read_b128 v[156:159], v239 offset:3072
	ds_read_b128 v[160:163], v239 offset:4096
	ds_read_b128 v[164:167], v239 offset:5120
	ds_read_b128 v[168:171], v239 offset:6144
	ds_read_b128 v[172:175], v239 offset:7168
	global_load_lds_dwordx4 v[176:177], off
	v_lshl_add_u64 v[176:177], s[0:1], 0, v[214:215]
	v_lshl_add_u64 v[176:177], v[176:177], 0, s[42:43]
	s_add_i32 m0, s58, 0xe000
	s_nop 0
	global_load_lds_dwordx4 v[176:177], off
	s_waitcnt lgkmcnt(8)
	s_barrier
	s_waitcnt lgkmcnt(0)
	s_setprio 1
	s_waitcnt lgkmcnt(0)
	v_mfma_f32_16x16x32_f16 v[124:127], v[128:131], v[144:147], v[124:127]
	v_mfma_f32_16x16x32_f16 v[120:123], v[136:139], v[144:147], v[120:123]
	v_mfma_f32_16x16x32_f16 v[108:111], v[128:131], v[152:155], v[108:111]
	v_mfma_f32_16x16x32_f16 v[104:107], v[136:139], v[152:155], v[104:107]
	v_mfma_f32_16x16x32_f16 v[92:95], v[128:131], v[160:163], v[92:95]
	v_mfma_f32_16x16x32_f16 v[88:91], v[136:139], v[160:163], v[88:91]
	v_mfma_f32_16x16x32_f16 v[76:79], v[128:131], v[168:171], v[76:79]
	v_mfma_f32_16x16x32_f16 v[72:75], v[136:139], v[168:171], v[72:75]
	v_mfma_f32_16x16x32_f16 v[124:127], v[132:135], v[148:151], v[124:127]
	v_mfma_f32_16x16x32_f16 v[120:123], v[140:143], v[148:151], v[120:123]
	v_mfma_f32_16x16x32_f16 v[108:111], v[132:135], v[156:159], v[108:111]
	v_mfma_f32_16x16x32_f16 v[104:107], v[140:143], v[156:159], v[104:107]
	v_mfma_f32_16x16x32_f16 v[92:95], v[132:135], v[164:167], v[92:95]
	v_mfma_f32_16x16x32_f16 v[88:91], v[140:143], v[164:167], v[88:91]
	v_mfma_f32_16x16x32_f16 v[76:79], v[132:135], v[172:175], v[76:79]
	v_mfma_f32_16x16x32_f16 v[72:75], v[140:143], v[172:175], v[72:75]
	s_setprio 0
	s_barrier
	s_add_i32 s42, 0, 0x14000
	s_add_i32 s39, s39, s31
	v_add_u32_e32 v188, s42, v238
	v_lshl_add_u64 v[192:193], s[36:37], 0, v[206:207]
	s_mov_b32 m0, s39
	ds_read_b128 v[176:179], v188
	ds_read_b128 v[180:183], v188 offset:1024
	ds_read_b128 v[184:187], v188 offset:2048
	ds_read_b128 v[188:191], v188 offset:3072
	global_load_lds_dwordx4 v[192:193], off
	v_lshl_add_u64 v[194:195], s[36:37], 0, v[210:211]
	s_add_i32 m0, s39, 0x2000
	s_nop 0
	global_load_lds_dwordx4 v[194:195], off
	s_barrier
	s_waitcnt lgkmcnt(0)
	s_setprio 1
	s_waitcnt lgkmcnt(0)
	v_mfma_f32_16x16x32_f16 v[116:119], v[176:179], v[144:147], v[116:119]
	v_mfma_f32_16x16x32_f16 v[112:115], v[184:187], v[144:147], v[112:115]
	v_mfma_f32_16x16x32_f16 v[100:103], v[176:179], v[152:155], v[100:103]
	v_mfma_f32_16x16x32_f16 v[96:99], v[184:187], v[152:155], v[96:99]
	v_mfma_f32_16x16x32_f16 v[84:87], v[176:179], v[160:163], v[84:87]
	v_mfma_f32_16x16x32_f16 v[80:83], v[184:187], v[160:163], v[80:83]
	v_mfma_f32_16x16x32_f16 v[68:71], v[176:179], v[168:171], v[68:71]
	v_mfma_f32_16x16x32_f16 v[64:67], v[184:187], v[168:171], v[64:67]
	v_mfma_f32_16x16x32_f16 v[116:119], v[180:183], v[148:151], v[116:119]
	v_mfma_f32_16x16x32_f16 v[112:115], v[188:191], v[148:151], v[112:115]
	v_mfma_f32_16x16x32_f16 v[100:103], v[180:183], v[156:159], v[100:103]
	v_mfma_f32_16x16x32_f16 v[96:99], v[188:191], v[156:159], v[96:99]
	v_mfma_f32_16x16x32_f16 v[84:87], v[180:183], v[164:167], v[84:87]
	v_mfma_f32_16x16x32_f16 v[80:83], v[188:191], v[164:167], v[80:83]
	v_mfma_f32_16x16x32_f16 v[68:71], v[180:183], v[172:175], v[68:71]
	v_mfma_f32_16x16x32_f16 v[64:67], v[188:191], v[172:175], v[64:67]
	s_setprio 0
	s_mov_b32 m0, s58
	v_lshl_add_u64 v[216:217], s[34:35], 0, v[204:205]
	s_barrier
	ds_read_b128 v[144:147], v239 offset:16384
	ds_read_b128 v[148:151], v239 offset:17408
	ds_read_b128 v[152:155], v239 offset:18432
	ds_read_b128 v[156:159], v239 offset:19456
	ds_read_b128 v[160:163], v239 offset:20480
	ds_read_b128 v[164:167], v239 offset:21504
	ds_read_b128 v[168:171], v239 offset:22528
	ds_read_b128 v[172:175], v239 offset:23552
	global_load_lds_dwordx4 v[216:217], off
	v_lshl_add_u64 v[218:219], s[34:35], 0, v[208:209]
	s_mov_b32 m0, s59
	s_nop 0
	global_load_lds_dwordx4 v[218:219], off
	s_barrier
; #define PG8_STAGE(bufoff, gbase, voff) do { _Pragma("unroll") for (int _i = 0; _i < 2; ++_i) \
;         __builtin_amdgcn_global_load_lds((const unsigned*)((const char*)(gbase) + (voff)[_i]), (LAS unsigned*)(lds + (bufoff) + ldsw + _i * 8192), 16, 0, 0); } while (0)
; #define PG8_LDA(dst, b, h) do { _Pragma("unroll") for (int m = 0; m < 4; ++m) _Pragma("unroll") for (int k = 0; k < 2; ++k) dst[m][k] = *(const LAS h16x8*)(lds + PG8_SA(b, h) + aoff + m * 2048 + k * 1024); } while (0)
; #define PG8_LDB(dst, b, h) do { _Pragma("unroll") for (int n = 0; n < 2; ++n) _Pragma("unroll") for (int k = 0; k < 2; ++k) dst[n][k] = *(const LAS h16x8*)(lds + PG8_SB(b, h) + boff + n * 2048 + k * 1024); } while (0)
; #define PG8_MMA(ai, bj, At, Bt) do { __builtin_amdgcn_s_setprio(1); _Pragma("unroll") for (int m = 0; m < 4; ++m) _Pragma("unroll") for (int n = 0; n < 2; ++n) _Pragma("unroll") for (int k = 0; k < 2; ++k) \
;         acc[ai][bj][m][n] = __builtin_amdgcn_mfma_f32_16x16x32_f16(Bt[n][k], At[m][k], acc[ai][bj][m][n], 0, 0, 0); __builtin_amdgcn_s_setprio(0); } while (0)
; #define PG8_WAIT_V(n) asm volatile("s_waitcnt vmcnt(" #n ")" ::: "memory")
; #define PG8_WAIT_L(n) asm volatile("s_waitcnt lgkmcnt(" #n ")" ::: "memory")
; #define PG8_BAR __builtin_amdgcn_s_barrier()
; #define PG8_SCHED __builtin_amdgcn_sched_barrier(0)
; __device__ __forceinline__ void gemm_phase(LAS unsigned char* lds, const Gemm g, const StaticOrder& S, const Epi& E) {
;     ...
;             PG8_BAR; PG8_WAIT_L(0); PG8_MMA(1, 0, At, B0); PG8_BAR; PG8_SCHED;
;             PG8_STAGE(PG8_SB(0, 1), b2 + hstepB, voffB);
;             PG8_WAIT_V(6); PG8_BAR; PG8_MMA(1, 1, At, B1); PG8_BAR;
;             PG8_LDB(B0, 1, 0); PG8_SCHED; PG8_LDA(At, 1, 0); PG8_STAGE(PG8_SA(0, 1), a2 + hstepA, voffA);
;             PG8_WAIT_L(8); PG8_BAR; PG8_WAIT_L(0); PG8_MMA(0, 0, At, B0); PG8_BAR; PG8_SCHED;
;             PG8_LDB(B1, 1, 1); PG8_STAGE(PG8_SB(1, 0), b3, voffB);
	s_waitcnt lgkmcnt(0)
	s_setprio 1
	s_waitcnt lgkmcnt(0)
	v_mfma_f32_16x16x32_f16 v[60:63], v[128:131], v[144:147], v[60:63]
	v_mfma_f32_16x16x32_f16 v[56:59], v[136:139], v[144:147], v[56:59]
	v_mfma_f32_16x16x32_f16 v[44:47], v[128:131], v[152:155], v[44:47]
	v_mfma_f32_16x16x32_f16 v[40:43], v[136:139], v[152:155], v[40:43]
	v_mfma_f32_16x16x32_f16 v[28:31], v[128:131], v[160:163], v[28:31]
	v_mfma_f32_16x16x32_f16 v[24:27], v[136:139], v[160:163], v[24:27]
	v_mfma_f32_16x16x32_f16 v[12:15], v[128:131], v[168:171], v[12:15]
	v_mfma_f32_16x16x32_f16 v[8:11], v[136:139], v[168:171], v[8:11]
	v_mfma_f32_16x16x32_f16 v[60:63], v[132:135], v[148:151], v[60:63]
	v_mfma_f32_16x16x32_f16 v[56:59], v[140:143], v[148:151], v[56:59]
	v_mfma_f32_16x16x32_f16 v[44:47], v[132:135], v[156:159], v[44:47]
	v_mfma_f32_16x16x32_f16 v[40:43], v[140:143], v[156:159], v[40:43]
	v_mfma_f32_16x16x32_f16 v[28:31], v[132:135], v[164:167], v[28:31]
	v_mfma_f32_16x16x32_f16 v[24:27], v[140:143], v[164:167], v[24:27]
	v_mfma_f32_16x16x32_f16 v[12:15], v[132:135], v[172:175], v[12:15]
	v_mfma_f32_16x16x32_f16 v[8:11], v[140:143], v[172:175], v[8:11]
	s_setprio 0
	s_barrier
	s_add_u32 s36, s36, s18
	s_addc_u32 s37, s37, s19
	s_add_i32 s39, s42, s31
	v_lshl_add_u64 v[220:221], s[36:37], 0, v[206:207]
	s_mov_b32 m0, s39
	v_lshl_add_u64 v[222:223], s[36:37], 0, v[210:211]
	global_load_lds_dwordx4 v[220:221], off
	s_add_i32 m0, s39, 0x2000
	s_nop 0
	global_load_lds_dwordx4 v[222:223], off
	s_waitcnt vmcnt(6)
	s_barrier
	s_setprio 1
	v_mfma_f32_16x16x32_f16 v[52:55], v[176:179], v[144:147], v[52:55]
	v_mfma_f32_16x16x32_f16 v[48:51], v[184:187], v[144:147], v[48:51]
	v_mfma_f32_16x16x32_f16 v[36:39], v[176:179], v[152:155], v[36:39]
	v_mfma_f32_16x16x32_f16 v[32:35], v[184:187], v[152:155], v[32:35]
	v_mfma_f32_16x16x32_f16 v[20:23], v[176:179], v[160:163], v[20:23]
	v_mfma_f32_16x16x32_f16 v[16:19], v[184:187], v[160:163], v[16:19]
	v_mfma_f32_16x16x32_f16 v[4:7], v[176:179], v[168:171], v[4:7]
	v_mfma_f32_16x16x32_f16 v[0:3], v[184:187], v[168:171], v[0:3]
	v_mfma_f32_16x16x32_f16 v[52:55], v[180:183], v[148:151], v[52:55]
	v_mfma_f32_16x16x32_f16 v[48:51], v[188:191], v[148:151], v[48:51]
	v_mfma_f32_16x16x32_f16 v[36:39], v[180:183], v[156:159], v[36:39]
	v_mfma_f32_16x16x32_f16 v[32:35], v[188:191], v[156:159], v[32:35]
	v_mfma_f32_16x16x32_f16 v[20:23], v[180:183], v[164:167], v[20:23]
	v_mfma_f32_16x16x32_f16 v[16:19], v[188:191], v[164:167], v[16:19]
	v_mfma_f32_16x16x32_f16 v[4:7], v[180:183], v[172:175], v[4:7]
	v_mfma_f32_16x16x32_f16 v[0:3], v[188:191], v[172:175], v[0:3]
	s_setprio 0
	s_add_i32 s36, 0, 0x18000
	v_add_u32_e32 v140, s36, v238
	s_barrier
	ds_read_b128 v[128:131], v140
	ds_read_b128 v[132:135], v140 offset:1024
	ds_read_b128 v[136:139], v140 offset:2048
	ds_read_b128 v[140:143], v140 offset:3072
	s_add_u32 s34, s34, s16
	s_addc_u32 s35, s35, s17
	s_mov_b32 m0, s60
	v_lshl_add_u64 v[176:177], s[34:35], 0, v[204:205]
	ds_read_b128 v[144:147], v239 offset:32768
	ds_read_b128 v[148:151], v239 offset:33792
	ds_read_b128 v[152:155], v239 offset:34816
	ds_read_b128 v[156:159], v239 offset:35840
	ds_read_b128 v[160:163], v239 offset:36864
	ds_read_b128 v[164:167], v239 offset:37888
	ds_read_b128 v[168:171], v239 offset:38912
	ds_read_b128 v[172:175], v239 offset:39936
	global_load_lds_dwordx4 v[176:177], off
	v_lshl_add_u64 v[176:177], s[34:35], 0, v[208:209]
	s_mov_b32 m0, s61
	s_nop 0
	global_load_lds_dwordx4 v[176:177], off
	s_waitcnt lgkmcnt(8)
	s_barrier
	s_waitcnt lgkmcnt(0)
	s_setprio 1
	s_waitcnt lgkmcnt(0)
	v_mfma_f32_16x16x32_f16 v[124:127], v[128:131], v[144:147], v[124:127]
	v_mfma_f32_16x16x32_f16 v[120:123], v[136:139], v[144:147], v[120:123]
	v_mfma_f32_16x16x32_f16 v[108:111], v[128:131], v[152:155], v[108:111]
	v_mfma_f32_16x16x32_f16 v[104:107], v[136:139], v[152:155], v[104:107]
	v_mfma_f32_16x16x32_f16 v[92:95], v[128:131], v[160:163], v[92:95]
	v_mfma_f32_16x16x32_f16 v[88:91], v[136:139], v[160:163], v[88:91]
	v_mfma_f32_16x16x32_f16 v[76:79], v[128:131], v[168:171], v[76:79]
	v_mfma_f32_16x16x32_f16 v[72:75], v[136:139], v[168:171], v[72:75]
	v_mfma_f32_16x16x32_f16 v[124:127], v[132:135], v[148:151], v[124:127]
	v_mfma_f32_16x16x32_f16 v[120:123], v[140:143], v[148:151], v[120:123]
	v_mfma_f32_16x16x32_f16 v[108:111], v[132:135], v[156:159], v[108:111]
	v_mfma_f32_16x16x32_f16 v[104:107], v[140:143], v[156:159], v[104:107]
	v_mfma_f32_16x16x32_f16 v[92:95], v[132:135], v[164:167], v[92:95]
	v_mfma_f32_16x16x32_f16 v[88:91], v[140:143], v[164:167], v[88:91]
	v_mfma_f32_16x16x32_f16 v[76:79], v[132:135], v[172:175], v[76:79]
	v_mfma_f32_16x16x32_f16 v[72:75], v[140:143], v[172:175], v[72:75]
	s_setprio 0
	s_barrier
	s_add_i32 s34, 0, 0x1c000
	s_add_i32 s35, s36, s31
	v_add_u32_e32 v188, s34, v238
	v_lshl_add_u64 v[192:193], v[192:193], 0, s[80:81]
	s_mov_b32 m0, s35
	ds_read_b128 v[176:179], v188
	ds_read_b128 v[180:183], v188 offset:1024
	ds_read_b128 v[184:187], v188 offset:2048
	ds_read_b128 v[188:191], v188 offset:3072
	global_load_lds_dwordx4 v[192:193], off
	v_lshl_add_u64 v[192:193], v[194:195], 0, s[80:81]
	s_add_i32 m0, s35, 0x2000
	s_nop 0
	global_load_lds_dwordx4 v[192:193], off
	s_barrier
; __device__ __forceinline__ u32x4 pack8(f32x4 a, f32x4 b) { u32x4 w; w.x = pk2(a[0], a[1]); w.y = pk2(a[2], a[3]); w.z = pk2(b[0], b[1]); w.w = pk2(b[2], b[3]); return w; }
; #define PG8_STAGE(bufoff, gbase, voff) do { _Pragma("unroll") for (int _i = 0; _i < 2; ++_i) \
;         __builtin_amdgcn_global_load_lds((const unsigned*)((const char*)(gbase) + (voff)[_i]), (LAS unsigned*)(lds + (bufoff) + ldsw + _i * 8192), 16, 0, 0); } while (0)
; #define PG8_LDA(dst, b, h) do { _Pragma("unroll") for (int m = 0; m < 4; ++m) _Pragma("unroll") for (int k = 0; k < 2; ++k) dst[m][k] = *(const LAS h16x8*)(lds + PG8_SA(b, h) + aoff + m * 2048 + k * 1024); } while (0)
; #define PG8_MMA(ai, bj, At, Bt) do { __builtin_amdgcn_s_setprio(1); _Pragma("unroll") for (int m = 0; m < 4; ++m) _Pragma("unroll") for (int n = 0; n < 2; ++n) _Pragma("unroll") for (int k = 0; k < 2; ++k) \
;         acc[ai][bj][m][n] = __builtin_amdgcn_mfma_f32_16x16x32_f16(Bt[n][k], At[m][k], acc[ai][bj][m][n], 0, 0, 0); __builtin_amdgcn_s_setprio(0); } while (0)
; #define PG8_WAIT_V(n) asm volatile("s_waitcnt vmcnt(" #n ")" ::: "memory")
; #define PG8_WAIT_L(n) asm volatile("s_waitcnt lgkmcnt(" #n ")" ::: "memory")
; #define PG8_BAR __builtin_amdgcn_s_barrier()
; #define PG8_SCHED __builtin_amdgcn_sched_barrier(0)
;     __device__ __forceinline__ void operator()(const f32x4 (&acc)[2][2][4][2], const Unit& u, int wr, int wc, int fr, int fq) const {
;     ...
;                     } else if (mode == E_ST16) {
;                         *(u32x4*)((h16*)(ws + F_U16) + (size_t)rowl * 5632 + col) = pack8(v0, v1);
; __device__ __forceinline__ void gemm_phase(LAS unsigned char* lds, const Gemm g, const StaticOrder& S, const Epi& E) {
;     ...
;             PG8_BAR; PG8_WAIT_L(0); PG8_MMA(0, 1, At, B1); PG8_BAR;
;             PG8_LDA(At, 1, 1); PG8_STAGE(PG8_SA(1, 0), a3, voffA);
;             PG8_BAR; PG8_WAIT_L(0); PG8_MMA(1, 0, At, B0); PG8_BAR; PG8_SCHED;
;             PG8_STAGE(PG8_SB(1, 1), b3 + hstepB, voffB);
;             PG8_WAIT_V(6); PG8_BAR; PG8_MMA(1, 1, At, B1); PG8_BAR;
;         }
;         E(acc, cur, wr, wc, fr, fq);
	s_waitcnt lgkmcnt(0)
	s_setprio 1
	s_waitcnt lgkmcnt(0)
	v_mfma_f32_16x16x32_f16 v[116:119], v[176:179], v[144:147], v[116:119]
	v_mfma_f32_16x16x32_f16 v[112:115], v[184:187], v[144:147], v[112:115]
	v_mfma_f32_16x16x32_f16 v[100:103], v[176:179], v[152:155], v[100:103]
	v_mfma_f32_16x16x32_f16 v[96:99], v[184:187], v[152:155], v[96:99]
	v_mfma_f32_16x16x32_f16 v[84:87], v[176:179], v[160:163], v[84:87]
	v_mfma_f32_16x16x32_f16 v[80:83], v[184:187], v[160:163], v[80:83]
	v_mfma_f32_16x16x32_f16 v[68:71], v[176:179], v[168:171], v[68:71]
	v_mfma_f32_16x16x32_f16 v[64:67], v[184:187], v[168:171], v[64:67]
	v_mfma_f32_16x16x32_f16 v[116:119], v[180:183], v[148:151], v[116:119]
	v_mfma_f32_16x16x32_f16 v[112:115], v[188:191], v[148:151], v[112:115]
	v_mfma_f32_16x16x32_f16 v[100:103], v[180:183], v[156:159], v[100:103]
	v_mfma_f32_16x16x32_f16 v[96:99], v[188:191], v[156:159], v[96:99]
	v_mfma_f32_16x16x32_f16 v[84:87], v[180:183], v[164:167], v[84:87]
	v_mfma_f32_16x16x32_f16 v[80:83], v[188:191], v[164:167], v[80:83]
	v_mfma_f32_16x16x32_f16 v[68:71], v[180:183], v[172:175], v[68:71]
	v_mfma_f32_16x16x32_f16 v[64:67], v[188:191], v[172:175], v[64:67]
	s_setprio 0
	s_mov_b32 m0, s62
	v_lshl_add_u64 v[192:193], v[216:217], 0, s[80:81]
	s_barrier
	ds_read_b128 v[144:147], v239 offset:49152
	ds_read_b128 v[148:151], v239 offset:50176
	ds_read_b128 v[152:155], v239 offset:51200
	ds_read_b128 v[156:159], v239 offset:52224
	ds_read_b128 v[160:163], v239 offset:53248
	ds_read_b128 v[164:167], v239 offset:54272
	ds_read_b128 v[168:171], v239 offset:55296
	ds_read_b128 v[172:175], v239 offset:56320
	global_load_lds_dwordx4 v[192:193], off
	v_lshl_add_u64 v[192:193], v[218:219], 0, s[80:81]
	s_mov_b32 m0, s63
	s_nop 0
	global_load_lds_dwordx4 v[192:193], off
	s_barrier
	s_waitcnt lgkmcnt(0)
	s_setprio 1
	s_waitcnt lgkmcnt(0)
	v_mfma_f32_16x16x32_f16 v[60:63], v[128:131], v[144:147], v[60:63]
	v_mfma_f32_16x16x32_f16 v[56:59], v[136:139], v[144:147], v[56:59]
	v_mfma_f32_16x16x32_f16 v[44:47], v[128:131], v[152:155], v[44:47]
	v_mfma_f32_16x16x32_f16 v[40:43], v[136:139], v[152:155], v[40:43]
	v_mfma_f32_16x16x32_f16 v[28:31], v[128:131], v[160:163], v[28:31]
	v_mfma_f32_16x16x32_f16 v[24:27], v[136:139], v[160:163], v[24:27]
	v_mfma_f32_16x16x32_f16 v[12:15], v[128:131], v[168:171], v[12:15]
	v_mfma_f32_16x16x32_f16 v[8:11], v[136:139], v[168:171], v[8:11]
	v_mfma_f32_16x16x32_f16 v[60:63], v[132:135], v[148:151], v[60:63]
	v_mfma_f32_16x16x32_f16 v[56:59], v[140:143], v[148:151], v[56:59]
	v_mfma_f32_16x16x32_f16 v[44:47], v[132:135], v[156:159], v[44:47]
	v_mfma_f32_16x16x32_f16 v[40:43], v[140:143], v[156:159], v[40:43]
	v_mfma_f32_16x16x32_f16 v[28:31], v[132:135], v[164:167], v[28:31]
	v_mfma_f32_16x16x32_f16 v[24:27], v[140:143], v[164:167], v[24:27]
	v_mfma_f32_16x16x32_f16 v[12:15], v[132:135], v[172:175], v[12:15]
	v_mfma_f32_16x16x32_f16 v[8:11], v[140:143], v[172:175], v[8:11]
	s_setprio 0
	s_barrier
	s_add_i32 s34, s34, s31
	v_lshl_add_u64 v[128:129], v[220:221], 0, s[80:81]
	s_mov_b32 m0, s34
	s_nop 0
	global_load_lds_dwordx4 v[128:129], off
	v_lshl_add_u64 v[128:129], v[222:223], 0, s[80:81]
	s_add_i32 m0, s34, 0x2000
	s_nop 0
	global_load_lds_dwordx4 v[128:129], off
	s_waitcnt vmcnt(6)
	s_barrier
	s_setprio 1
	v_mfma_f32_16x16x32_f16 v[52:55], v[176:179], v[144:147], v[52:55]
	v_mfma_f32_16x16x32_f16 v[48:51], v[184:187], v[144:147], v[48:51]
	v_mfma_f32_16x16x32_f16 v[36:39], v[176:179], v[152:155], v[36:39]
	v_mfma_f32_16x16x32_f16 v[32:35], v[184:187], v[152:155], v[32:35]
	v_mfma_f32_16x16x32_f16 v[20:23], v[176:179], v[160:163], v[20:23]
	v_mfma_f32_16x16x32_f16 v[16:19], v[184:187], v[160:163], v[16:19]
	v_mfma_f32_16x16x32_f16 v[4:7], v[176:179], v[168:171], v[4:7]
	v_mfma_f32_16x16x32_f16 v[0:3], v[184:187], v[168:171], v[0:3]
	v_mfma_f32_16x16x32_f16 v[52:55], v[180:183], v[148:151], v[52:55]
	v_mfma_f32_16x16x32_f16 v[48:51], v[188:191], v[148:151], v[48:51]
	v_mfma_f32_16x16x32_f16 v[36:39], v[180:183], v[156:159], v[36:39]
	v_mfma_f32_16x16x32_f16 v[32:35], v[188:191], v[156:159], v[32:35]
	v_mfma_f32_16x16x32_f16 v[20:23], v[180:183], v[164:167], v[20:23]
	v_mfma_f32_16x16x32_f16 v[16:19], v[188:191], v[164:167], v[16:19]
	v_mfma_f32_16x16x32_f16 v[4:7], v[180:183], v[172:175], v[4:7]
	v_mfma_f32_16x16x32_f16 v[0:3], v[188:191], v[172:175], v[0:3]
	s_setprio 0
	s_add_u32 s0, s0, 0x100
	s_addc_u32 s1, s1, 0
	s_add_u32 s27, s27, 0x100
	s_addc_u32 s33, s33, 0
	s_cmp_ge_u32 s38, s64
	s_mov_b32 s34, s38
	s_barrier
	s_cbranch_scc0 .LBB0_762
	s_lshl_b32 s0, s84, 8
	s_or_b32 s27, s0, s65
	v_lshl_add_u32 v240, s30, 8, v200
	v_or_b32_e32 v216, s27, v202
	s_cmp_eq_u32 s93, 3
	s_cbranch_scc1 .Lst16_fast
	s_mov_b64 s[0:1], -1
	s_mov_b64 s[34:35], 0
	s_cmp_lt_i32 s93, 2
	s_mov_b64 s[36:37], 0
	s_cbranch_scc1 .LBB0_831
; __device__ __forceinline__ size_t xrow(int row) { return (size_t)(row >> 11) * 2049 + 1 + (row & 2047); }
; __device__ __forceinline__ u32x4 pack8(f32x4 a, f32x4 b) { u32x4 w; w.x = pk2(a[0], a[1]); w.y = pk2(a[2], a[3]); w.z = pk2(b[0], b[1]); w.w = pk2(b[2], b[3]); return w; }
;     __device__ __forceinline__ void operator()(const f32x4 (&acc)[2][2][4][2], const Unit& u, int wr, int wc, int fr, int fq) const {
;     ...
;         if (mode == E_RESID) {
;             u32x4 xr[2][4][2];
; #pragma unroll
;             for (int ai = 0; ai < 2; ++ai)
; #pragma unroll
;                 for (int m = 0; m < 4; ++m) {
;                     const int rowg = rowl0 + ai * HALF + m * 16 + pm0 * BM;
;                     const h16* xp = (const h16*)(ws + OFF_X16) + xrow(rowg) * 1024 + colt;
; #pragma unroll
;                     for (int bj = 0; bj < 2; ++bj) xr[ai][m][bj] = *(const u32x4*)(xp + bj * HALF);
;                 }
; #pragma unroll
;             for (int ai = 0; ai < 2; ++ai)
; #pragma unroll
;                 for (int m = 0; m < 4; ++m) {
;                     const int rowg = rowl0 + ai * HALF + m * 16 + pm0 * BM;
;                     float* dp0 = out + (size_t)rowg * 1024 + colt;
;                     h16* hp0 = (h16*)out + (size_t)rowg * 1024 + colt;
; #pragma unroll
;                     for (int bj = 0; bj < 2; ++bj) {
;                         float xf[8]; unpack8(xr[ai][m][bj], xf);
;                         const f32x4 v0 = acc[ai][bj][m][0], v1 = acc[ai][bj][m][1];
;                         f32x4 r0, r1;
; #pragma unroll
;                         for (int jj = 0; jj < 4; ++jj) { r0[jj] = DN_ALPHA * xf[jj] + v0[jj]; r1[jj] = DN_ALPHA * xf[4 + jj] + v1[jj]; }
;                         if (fin) { float* dp = dp0 + bj * HALF; *(f32x4*)dp = r0; *(f32x4*)(dp + 4) = r1; }
;                         else *(u32x4*)(hp0 + bj * HALF) = pack8(r0, r1);
;                     }
	s_cmp_eq_u32 s93, 2
	s_mov_b64 s[36:37], -1
	s_cbranch_scc0 .LBB0_830
	s_add_i32 s0, s30, s56
	v_lshl_add_u32 v220, s0, 8, v200
	v_ashrrev_i32_e32 v130, 11, v220
	v_and_b32_e32 v134, 0x7cf, v220
	v_ashrrev_i32_e32 v217, 31, v216
	v_readlane_b32 s0, v249, 8
	v_mul_hi_i32_i24_e32 v131, 0x801, v130
	v_mul_i32_i24_e32 v130, 0x801, v130
	v_add_u32_e32 v196, 1, v134
	v_lshlrev_b64 v[218:219], 1, v[216:217]
	v_readlane_b32 s1, v249, 9
	v_lshl_add_u64 v[132:133], v[130:131], 0, v[196:197]
	v_lshlrev_b64 v[132:133], 11, v[132:133]
	v_lshl_add_u64 v[128:129], s[0:1], 0, v[218:219]
	v_lshl_add_u64 v[132:133], v[128:129], 0, v[132:133]
	v_add_u32_e32 v196, 17, v134
	global_load_dwordx4 v[188:191], v[132:133], off
	global_load_dwordx4 v[184:187], v[132:133], off offset:256
	v_lshl_add_u64 v[132:133], v[130:131], 0, v[196:197]
	v_lshlrev_b64 v[132:133], 11, v[132:133]
	v_lshl_add_u64 v[132:133], v[128:129], 0, v[132:133]
	v_add_u32_e32 v196, 33, v134
	global_load_dwordx4 v[180:183], v[132:133], off
	global_load_dwordx4 v[176:179], v[132:133], off offset:256
	v_lshl_add_u64 v[132:133], v[130:131], 0, v[196:197]
	v_add_u32_e32 v196, 49, v134
	v_lshlrev_b64 v[132:133], 11, v[132:133]
	v_lshl_add_u64 v[130:131], v[130:131], 0, v[196:197]
	v_lshl_add_u64 v[132:133], v[128:129], 0, v[132:133]
	v_lshlrev_b64 v[130:131], 11, v[130:131]
	global_load_dwordx4 v[172:175], v[132:133], off
	global_load_dwordx4 v[168:171], v[132:133], off offset:256
	v_lshl_add_u64 v[130:131], v[128:129], 0, v[130:131]
	v_add_u32_e32 v132, 0x80, v220
	global_load_dwordx4 v[164:167], v[130:131], off
	global_load_dwordx4 v[160:163], v[130:131], off offset:256
	v_ashrrev_i32_e32 v130, 11, v132
	v_and_b32_e32 v132, 0x7cf, v132
	v_mul_hi_i32_i24_e32 v131, 0x801, v130
	v_mul_i32_i24_e32 v130, 0x801, v130
	v_add_u32_e32 v196, 1, v132
	v_lshl_add_u64 v[130:131], v[130:131], 0, v[196:197]
	v_lshlrev_b64 v[130:131], 11, v[130:131]
	v_lshl_add_u64 v[130:131], v[128:129], 0, v[130:131]
	v_add_u32_e32 v132, 0x90, v220
	global_load_dwordx4 v[156:159], v[130:131], off
	global_load_dwordx4 v[152:155], v[130:131], off offset:256
	v_ashrrev_i32_e32 v130, 11, v132
	v_and_b32_e32 v132, 0x7df, v132
	v_mul_hi_i32_i24_e32 v131, 0x801, v130
	v_mul_i32_i24_e32 v130, 0x801, v130
	v_add_u32_e32 v196, 1, v132
	v_lshl_add_u64 v[130:131], v[130:131], 0, v[196:197]
	v_lshlrev_b64 v[130:131], 11, v[130:131]
	v_lshl_add_u64 v[130:131], v[128:129], 0, v[130:131]
	v_add_u32_e32 v132, 0xa0, v220
	global_load_dwordx4 v[148:151], v[130:131], off
	global_load_dwordx4 v[144:147], v[130:131], off offset:256
	v_ashrrev_i32_e32 v130, 11, v132
	v_and_b32_e32 v132, 0x7ef, v132
	v_mul_hi_i32_i24_e32 v131, 0x801, v130
	v_mul_i32_i24_e32 v130, 0x801, v130
	v_add_u32_e32 v196, 1, v132
	v_lshl_add_u64 v[130:131], v[130:131], 0, v[196:197]
	v_lshlrev_b64 v[130:131], 11, v[130:131]
	v_lshl_add_u64 v[130:131], v[128:129], 0, v[130:131]
	v_add_u32_e32 v132, 0xb0, v220
	global_load_dwordx4 v[140:143], v[130:131], off
	global_load_dwordx4 v[136:139], v[130:131], off offset:256
	v_ashrrev_i32_e32 v130, 11, v132
	v_and_b32_e32 v132, 0x7ff, v132
	v_mul_hi_i32_i24_e32 v131, 0x801, v130
	v_mul_i32_i24_e32 v130, 0x801, v130
	v_add_u32_e32 v196, 1, v132
	v_lshl_add_u64 v[130:131], v[130:131], 0, v[196:197]
	v_lshlrev_b64 v[130:131], 11, v[130:131]
	v_lshl_add_u64 v[128:129], v[128:129], 0, v[130:131]
	global_load_dwordx4 v[132:135], v[128:129], off
	s_nop 0
	global_load_dwordx4 v[128:131], v[128:129], off offset:256
	v_ashrrev_i32_e32 v221, 31, v220
	v_readlane_b32 s0, v252, 45
	v_lshlrev_b64 v[192:193], 12, v[220:221]
	v_readlane_b32 s1, v252, 46
	v_readlane_b32 s36, v253, 57
	v_readlane_b32 s37, v253, 58
	v_lshl_add_u64 v[224:225], s[0:1], 0, v[192:193]
	s_mov_b32 s0, 0x3fd744fd
	v_cndmask_b32_e64 v196, 0, 1, s[36:37]
	v_lshl_add_u64 v[222:223], v[216:217], 2, v[224:225]
	s_andn2_b64 vcc, exec, s[36:37]
	s_mov_b64 s[36:37], -1
	s_waitcnt vmcnt(0)
	v_cvt_f32_f16_e32 v192, v188
	v_cvt_f32_f16_sdwa v193, v188 dst_sel:DWORD dst_unused:UNUSED_PAD src0_sel:WORD_1
	v_cvt_f32_f16_e32 v194, v190
	v_cvt_f32_f16_sdwa v195, v190 dst_sel:DWORD dst_unused:UNUSED_PAD src0_sel:WORD_1
	v_cvt_f32_f16_e32 v246, v189
	v_cvt_f32_f16_sdwa v247, v189 dst_sel:DWORD dst_unused:UNUSED_PAD src0_sel:WORD_1
	v_cvt_f32_f16_e32 v190, v191
	v_cvt_f32_f16_sdwa v191, v191 dst_sel:DWORD dst_unused:UNUSED_PAD src0_sel:WORD_1
	v_pk_fma_f32 v[192:193], v[192:193], s[0:1], v[124:125] op_sel_hi:[1,0,1]
	v_pk_fma_f32 v[188:189], v[194:195], s[0:1], v[120:121] op_sel_hi:[1,0,1]
	v_pk_fma_f32 v[194:195], v[246:247], s[0:1], v[126:127] op_sel_hi:[1,0,1]
	v_pk_fma_f32 v[190:191], v[190:191], s[0:1], v[122:123] op_sel_hi:[1,0,1]
	v_cmp_ne_u32_e64 s[0:1], 1, v196
	s_cbranch_vccnz .LBB0_767
	s_mov_b64 s[36:37], 0
	global_store_dwordx4 v[222:223], v[192:195], off
	global_store_dwordx4 v[222:223], v[188:191], off offset:16
